# prep: pool-fold dot products keep four 8-term groups of loads in flight per wait (was one group per round trip)
# baseline (speedup 1.0000x reference)
; DI void phase_prep(const Params& p, char* smem) {
;     ...
;   for (int e = blk__ * 256 + tid; e < 2 * 256 * 1024; e += gridDim.x * 256) {
;     const int l = e >> 18, r = e & 262143, cin = r >> 10, n = r & 1023, g = cin >> 6, c = cin & 63;
;     const float* pw = p.in[I_POOLW] + ((size_t)(l * 4 + g) * 64 + c) * 64;
;     const float* ps = p.in[I_POOLS] + l * 256 + g * 64;
;     const float* wb = p.in[I_BRP] + ((size_t)l * 256 + g * 64) * 1024 + n;
;     float s = 0.f;
;     for (int d = 0; d < 64; ++d) s += pw[d] * ps[d] * wb[(size_t)d * 1024];
.LBB0_299:
	v_and_b32_e32 v6, 0x3ff, v15
	v_lshlrev_b32_e32 v12, 2, v6
	v_ashrrev_i32_e32 v6, 18, v1
	v_lshlrev_b32_e32 v4, 2, v1
	v_lshlrev_b32_e32 v10, 8, v6
	v_ashrrev_i32_e32 v7, 31, v6
	v_and_b32_e32 v4, 0xc0000, v4
	v_lshrrev_b32_e32 v18, 16, v1
	v_lshlrev_b32_e32 v20, 2, v6
	v_ashrrev_i32_e32 v11, 31, v10
	v_lshlrev_b64 v[8:9], 20, v[6:7]
	v_lshrrev_b32_e32 v13, 8, v1
	v_or3_b32 v8, v8, v4, v12
	v_lshlrev_b64 v[10:11], 2, v[10:11]
	v_and_or_b32 v12, v18, 3, v20
	v_and_or_b32 v10, v13, s19, v10
	v_ashrrev_i32_e32 v13, 31, v12
	v_lshrrev_b32_e32 v19, 2, v1
	v_lshlrev_b64 v[12:13], 14, v[12:13]
	v_and_or_b32 v12, v19, s20, v12
	v_lshrrev_b32_e32 v17, 10, v1
	v_lshl_add_u64 v[8:9], s[10:11], 0, v[8:9]
	v_lshl_add_u64 v[10:11], s[6:7], 0, v[10:11]
	v_lshl_add_u64 v[12:13], s[4:5], 0, v[12:13]
	s_mov_b64 s[14:15], 0
	s_mov_b64 s[16:17], 0
	v_mov_b32_e32 v4, 0
	v_mov_b32_e32 v224, 0x2000
	v_mov_b32_e32 v225, 0
	v_mov_b32_e32 v226, 0x4000
	v_mov_b32_e32 v227, 0
	v_mov_b32_e32 v228, 0x6000
	v_mov_b32_e32 v229, 0
	v_mov_b32_e32 v230, 0x7000
	v_mov_b32_e32 v231, 0
; DI u16 f2bf(float a) { return (u16)(pack2(a, 0.f) & 0xffffu); }
; DI void phase_prep(const Params& p, char* smem) {
;     ...
;   for (int e = blk__ * 256 + tid; e < 2 * 256 * 1024; e += gridDim.x * 256) {
;     const int l = e >> 18, r = e & 262143, cin = r >> 10, n = r & 1023, g = cin >> 6, c = cin & 63;
;     const float* pw = p.in[I_POOLW] + ((size_t)(l * 4 + g) * 64 + c) * 64;
;     const float* ps = p.in[I_POOLS] + l * 256 + g * 64;
;     const float* wb = p.in[I_BRP] + ((size_t)l * 256 + g * 64) * 1024 + n;
;     float s = 0.f;
;     for (int d = 0; d < 64; ++d) s += pw[d] * ps[d] * wb[(size_t)d * 1024];
;     ((u16*)(p.ws + OFF_W + (size_t)l * W_LAYER + WO_BRP))[(size_t)n * 256 + cin] = f2bf(s);
.LBB0_300:
	v_lshl_add_u64 v[34:35], v[12:13], 0, s[14:15]
	v_lshl_add_u64 v[38:39], v[8:9], 0, s[16:17]
	v_lshl_add_u64 v[36:37], v[10:11], 0, s[14:15]
	global_load_dwordx4 v[100:103], v[34:35], off offset:16
	global_load_dwordx4 v[104:107], v[34:35], off
	global_load_dwordx4 v[108:111], v[36:37], off offset:16
	global_load_dwordx4 v[112:115], v[36:37], off
	global_load_dword v116, v[38:39], off
	v_lshl_add_u64 v[34:35], v[38:39], 0, v[224:225]
	v_lshl_add_u64 v[36:37], v[38:39], 0, v[226:227]
	v_lshl_add_u64 v[40:41], v[38:39], 0, v[228:229]
	global_load_dword v117, v[34:35], off offset:-4096
	global_load_dword v118, v[34:35], off
	global_load_dword v119, v[36:37], off offset:-4096
	global_load_dword v120, v[36:37], off
	v_lshl_add_u64 v[34:35], v[38:39], 0, v[230:231]
	global_load_dword v121, v[40:41], off offset:-4096
	global_load_dword v122, v[40:41], off
	global_load_dword v123, v[34:35], off
	s_add_u32 s16, s16, 0x8000
	s_addc_u32 s17, s17, 0
	s_add_u32 s14, s14, 32
	s_addc_u32 s15, s15, 0
	v_lshl_add_u64 v[34:35], v[12:13], 0, s[14:15]
	v_lshl_add_u64 v[38:39], v[8:9], 0, s[16:17]
	v_lshl_add_u64 v[36:37], v[10:11], 0, s[14:15]
	global_load_dwordx4 v[128:131], v[34:35], off offset:16
	global_load_dwordx4 v[132:135], v[34:35], off
	global_load_dwordx4 v[136:139], v[36:37], off offset:16
	global_load_dwordx4 v[140:143], v[36:37], off
	global_load_dword v144, v[38:39], off
	v_lshl_add_u64 v[34:35], v[38:39], 0, v[224:225]
	v_lshl_add_u64 v[36:37], v[38:39], 0, v[226:227]
	v_lshl_add_u64 v[40:41], v[38:39], 0, v[228:229]
	global_load_dword v145, v[34:35], off offset:-4096
	global_load_dword v146, v[34:35], off
	global_load_dword v147, v[36:37], off offset:-4096
	global_load_dword v148, v[36:37], off
	v_lshl_add_u64 v[34:35], v[38:39], 0, v[230:231]
	global_load_dword v149, v[40:41], off offset:-4096
	global_load_dword v150, v[40:41], off
	global_load_dword v151, v[34:35], off
	s_add_u32 s16, s16, 0x8000
	s_addc_u32 s17, s17, 0
	s_add_u32 s14, s14, 32
	s_addc_u32 s15, s15, 0
	v_lshl_add_u64 v[34:35], v[12:13], 0, s[14:15]
	v_lshl_add_u64 v[38:39], v[8:9], 0, s[16:17]
	v_lshl_add_u64 v[36:37], v[10:11], 0, s[14:15]
	global_load_dwordx4 v[164:167], v[34:35], off offset:16
	global_load_dwordx4 v[168:171], v[34:35], off
	global_load_dwordx4 v[172:175], v[36:37], off offset:16
	global_load_dwordx4 v[176:179], v[36:37], off
	global_load_dword v180, v[38:39], off
	v_lshl_add_u64 v[34:35], v[38:39], 0, v[224:225]
	v_lshl_add_u64 v[36:37], v[38:39], 0, v[226:227]
	v_lshl_add_u64 v[40:41], v[38:39], 0, v[228:229]
	global_load_dword v181, v[34:35], off offset:-4096
	global_load_dword v182, v[34:35], off
	global_load_dword v183, v[36:37], off offset:-4096
	global_load_dword v184, v[36:37], off
	v_lshl_add_u64 v[34:35], v[38:39], 0, v[230:231]
	global_load_dword v185, v[40:41], off offset:-4096
	global_load_dword v186, v[40:41], off
	global_load_dword v187, v[34:35], off
	s_add_u32 s16, s16, 0x8000
	s_addc_u32 s17, s17, 0
	s_add_u32 s14, s14, 32
	s_addc_u32 s15, s15, 0
	v_lshl_add_u64 v[34:35], v[12:13], 0, s[14:15]
	v_lshl_add_u64 v[38:39], v[8:9], 0, s[16:17]
	v_lshl_add_u64 v[36:37], v[10:11], 0, s[14:15]
	global_load_dwordx4 v[188:191], v[34:35], off offset:16
	global_load_dwordx4 v[192:195], v[34:35], off
	global_load_dwordx4 v[196:199], v[36:37], off offset:16
	global_load_dwordx4 v[200:203], v[36:37], off
	global_load_dword v204, v[38:39], off
	v_lshl_add_u64 v[34:35], v[38:39], 0, v[224:225]
	v_lshl_add_u64 v[36:37], v[38:39], 0, v[226:227]
	v_lshl_add_u64 v[40:41], v[38:39], 0, v[228:229]
	global_load_dword v205, v[34:35], off offset:-4096
	global_load_dword v206, v[34:35], off
	global_load_dword v207, v[36:37], off offset:-4096
	global_load_dword v208, v[36:37], off
	v_lshl_add_u64 v[34:35], v[38:39], 0, v[230:231]
	global_load_dword v209, v[40:41], off offset:-4096
	global_load_dword v210, v[40:41], off
	global_load_dword v211, v[34:35], off
	s_add_u32 s16, s16, 0x8000
	s_addc_u32 s17, s17, 0
	s_add_u32 s14, s14, 32
	s_addc_u32 s15, s15, 0
	s_waitcnt vmcnt(36)
	v_mul_f32_e32 v100, v100, v108
	v_mul_f32_e32 v104, v104, v112
	v_mul_f32_e32 v105, v105, v113
	v_fmac_f32_e32 v4, v104, v116
	v_mul_f32_e32 v106, v106, v114
	v_mul_f32_e32 v107, v107, v115
	v_mul_f32_e32 v101, v101, v109
	v_mul_f32_e32 v102, v102, v110
	v_mul_f32_e32 v103, v103, v111
	v_fmac_f32_e32 v4, v105, v117
	v_fmac_f32_e32 v4, v106, v118
	v_fmac_f32_e32 v4, v107, v119
	v_fmac_f32_e32 v4, v100, v120
	v_fmac_f32_e32 v4, v101, v121
	v_fmac_f32_e32 v4, v102, v122
	v_fmac_f32_e32 v4, v103, v123
	s_waitcnt vmcnt(24)
	v_mul_f32_e32 v128, v128, v136
	v_mul_f32_e32 v132, v132, v140
	v_mul_f32_e32 v133, v133, v141
	v_fmac_f32_e32 v4, v132, v144
	v_mul_f32_e32 v134, v134, v142
	v_mul_f32_e32 v135, v135, v143
	v_mul_f32_e32 v129, v129, v137
	v_mul_f32_e32 v130, v130, v138
	v_mul_f32_e32 v131, v131, v139
	v_fmac_f32_e32 v4, v133, v145
	v_fmac_f32_e32 v4, v134, v146
	v_fmac_f32_e32 v4, v135, v147
	v_fmac_f32_e32 v4, v128, v148
	v_fmac_f32_e32 v4, v129, v149
	v_fmac_f32_e32 v4, v130, v150
	v_fmac_f32_e32 v4, v131, v151
	s_waitcnt vmcnt(12)
	v_mul_f32_e32 v164, v164, v172
	v_mul_f32_e32 v168, v168, v176
	v_mul_f32_e32 v169, v169, v177
	v_fmac_f32_e32 v4, v168, v180
	v_mul_f32_e32 v170, v170, v178
	v_mul_f32_e32 v171, v171, v179
	v_mul_f32_e32 v165, v165, v173
	v_mul_f32_e32 v166, v166, v174
	v_mul_f32_e32 v167, v167, v175
	v_fmac_f32_e32 v4, v169, v181
	v_fmac_f32_e32 v4, v170, v182
	v_fmac_f32_e32 v4, v171, v183
	v_fmac_f32_e32 v4, v164, v184
	v_fmac_f32_e32 v4, v165, v185
	v_fmac_f32_e32 v4, v166, v186
	v_fmac_f32_e32 v4, v167, v187
	s_waitcnt vmcnt(0)
	v_mul_f32_e32 v188, v188, v196
	v_mul_f32_e32 v192, v192, v200
	v_mul_f32_e32 v193, v193, v201
	v_fmac_f32_e32 v4, v192, v204
	v_mul_f32_e32 v194, v194, v202
	v_mul_f32_e32 v195, v195, v203
	v_mul_f32_e32 v189, v189, v197
	v_mul_f32_e32 v190, v190, v198
	v_mul_f32_e32 v191, v191, v199
	v_fmac_f32_e32 v4, v193, v205
	v_fmac_f32_e32 v4, v194, v206
	v_fmac_f32_e32 v4, v195, v207
	v_fmac_f32_e32 v4, v188, v208
	v_fmac_f32_e32 v4, v189, v209
	v_fmac_f32_e32 v4, v190, v210
	v_fmac_f32_e32 v4, v191, v211
	s_cmp_eq_u32 s16, 0x40000
	s_cbranch_scc0 .LBB0_300
	v_and_b32_e32 v8, 0x3ff, v1
	v_cvt_pk_bf16_f32 v9, v4, s0
	v_mad_i64_i32 v[6:7], s[14:15], v6, s27, v[2:3]
	v_lshlrev_b32_e32 v4, 9, v8
	v_lshl_add_u64 v[6:7], v[6:7], 0, v[4:5]
	v_lshlrev_b32_sdwa v4, v16, v17 dst_sel:DWORD dst_unused:UNUSED_PAD src0_sel:DWORD src1_sel:BYTE_0
	v_lshl_add_u64 v[6:7], v[6:7], 0, v[4:5]
	v_add_co_u32_e32 v6, vcc, 0x1461000, v6
	v_add_u32_e32 v1, s18, v1
	s_nop 0
	v_addc_co_u32_e32 v7, vcc, 0, v7, vcc
	v_cmp_lt_i32_e32 vcc, s28, v1
	s_or_b64 s[12:13], vcc, s[12:13]
	v_add_u16_e32 v15, s18, v15
	global_store_short v[6:7], v9, off
	s_andn2_b64 exec, exec, s[12:13]
	s_cbranch_execnz .LBB0_299
